# work queue order: SGU blocks pulled first (heavy-first), then LRU pass 2, pooling, output norm
# baseline (speedup 1.0000x reference)
.LBB0_575:
	s_or_b64 exec, exec, s[4:5]
	v_mov_b32_e32 v0, s85
	s_waitcnt lgkmcnt(0)
	s_barrier
	ds_read_b32 v0, v0
	s_waitcnt lgkmcnt(0)
	s_barrier
	v_readfirstlane_b32 s28, v0
	s_nop 0
	s_cmpk_lt_u32 s28, 0x180
	s_cbranch_scc0 .Lq_map_done
	s_addk_i32 s28, 0x100
	s_cmpk_lt_u32 s28, 0x180
	s_cbranch_scc1 .Lq_map_done
	s_addk_i32 s28, 0xfe80
.Lq_map_done:
	s_cmpk_gt_i32 s28, 0x2bf
	s_cselect_b64 s[54:55], -1, 0
	s_and_b64 vcc, exec, s[54:55]
	s_cbranch_vccnz .LBB0_572
	s_and_saveexec_b64 s[4:5], s[38:39]
	s_cbranch_execz .LBB0_579
	v_mov_b64_e32 v[0:1], s[92:93]
	s_waitcnt vmcnt(0)
	flat_atomic_add v78, v[0:1], v230 sc0
	s_or_b64 exec, exec, s[4:5]
	s_cmpk_gt_i32 s28, 0xff
	s_mov_b64 s[4:5], -1
	s_cbranch_scc1 .LBB0_580
